# rg_prompt A-fragment conv: taps j=0..2 of token blocks 1..3 (both K halves) rebuilt from the j=3 row loads by DPP row shifts (18 fewer row-gather loads per channel block)
# speedup vs baseline: 1.0173x; 1.0013x over previous
.LBB0_193:
	s_xor_b64 s[70:71], s[54:55], -1
	v_readlane_b32 s100, v255, 41
	s_nop 3
	s_cmp_lg_u32 s100, 0
	s_cbranch_scc1 .LBB0_192
	v_readlane_b32 s54, v254, 18
	s_or_b32 s80, s78, s54
	s_lshl_b32 s54, s80, 6
	s_ashr_i32 s55, s54, 31
	s_lshl_b64 s[78:79], s[54:55], 2
	v_readlane_b32 s82, v253, 13
	v_readlane_b32 s83, v253, 14
	s_add_u32 s84, s82, s78
	s_addc_u32 s85, s83, s79
	v_lshlrev_b32_e32 v144, 2, v88
	s_waitcnt lgkmcnt(0)
	v_lshl_add_u64 v[40:41], s[84:85], 0, v[144:145]
	s_movk_i32 s81, 0x1000
	v_add_co_u32_e32 v36, vcc, s81, v40
	s_mov_b64 s[82:83], 0x1000
	s_nop 0
	v_addc_co_u32_e32 v37, vcc, 0, v41, vcc
	v_add_co_u32_e32 v42, vcc, s33, v40
	v_lshl_add_u64 v[0:1], v[40:41], 0, s[82:83]
	s_nop 0
	v_addc_co_u32_e32 v43, vcc, 0, v41, vcc
	s_mov_b64 s[82:83], 0x2000
	global_load_dwordx4 v[8:11], v144, s[84:85] offset:16
	global_load_dwordx4 v[44:47], v144, s[84:85]
	global_load_dwordx4 v[28:31], v[42:43], off offset:-4096
	global_load_dwordx4 v[20:23], v[0:1], off offset:16
	v_lshl_add_u64 v[0:1], v[40:41], 0, s[82:83]
	s_mov_b64 s[82:83], 0x3000
	v_lshl_add_u64 v[12:13], v[40:41], 0, s[82:83]
	s_lshl_b64 s[82:83], s[54:55], 1
	v_add_co_u32_e32 v48, vcc, s87, v40
	v_lshl_add_u64 v[78:79], v[94:95], 0, s[82:83]
	s_nop 0
	v_addc_co_u32_e32 v49, vcc, 0, v41, vcc
	v_lshl_add_u64 v[50:51], v[96:97], 0, s[78:79]
	v_lshl_add_u64 v[38:39], v[78:79], 0, s[58:59]
	global_load_dwordx4 v[4:7], v[42:43], off
	s_nop 0
	global_load_dwordx4 v[0:3], v[0:1], off offset:16
	s_nop 0
	global_load_dwordx4 v[16:19], v[48:49], off
	s_nop 0
	global_load_dwordx4 v[12:15], v[12:13], off offset:16
	s_nop 0
	global_load_dwordx4 v[24:27], v[50:51], off offset:16
	global_load_dwordx4 v[32:35], v[50:51], off
	s_nop 0
	v_lshl_add_u64 v[38:39], v[78:79], 0, s[60:61]
	v_lshl_add_u64 v[74:75], v[78:79], 0, s[56:57]
	s_mov_b32 s100, 0xffff3a00
	s_mov_b32 s101, -1
	v_lshl_add_u64 v[242:243], v[74:75], 0, s[100:101]
	global_load_dwordx4 v[132:135], v[242:243], off
	s_mov_b32 s100, 0xffff7c00
	s_mov_b32 s101, -1
	v_lshl_add_u64 v[242:243], v[74:75], 0, s[100:101]
	global_load_dwordx4 v[136:139], v[242:243], off
	s_mov_b32 s100, 0xffffbe00
	s_mov_b32 s101, -1
	v_lshl_add_u64 v[242:243], v[74:75], 0, s[100:101]
	global_load_dwordx4 v[140:143], v[242:243], off
	s_mov_b32 s100, 0x0
	s_mov_b32 s101, 0
	v_lshl_add_u64 v[242:243], v[74:75], 0, s[100:101]
	global_load_dwordx4 v[162:165], v[242:243], off
	s_nop 0
	s_nop 0
	s_nop 0
	s_mov_b32 s100, 0x42000
	s_mov_b32 s101, 0
	v_lshl_add_u64 v[242:243], v[74:75], 0, s[100:101]
	global_load_dwordx4 v[180:183], v[242:243], off
	s_nop 0
	s_nop 0
	s_nop 0
	s_mov_b32 s100, 0x84000
	s_mov_b32 s101, 0
	v_lshl_add_u64 v[242:243], v[74:75], 0, s[100:101]
	global_load_dwordx4 v[216:219], v[242:243], off
	s_nop 0
	s_nop 0
	s_nop 0
	s_mov_b32 s100, 0xc6000
	s_mov_b32 s101, 0
	v_lshl_add_u64 v[242:243], v[74:75], 0, s[100:101]
	global_load_dwordx4 v[232:235], v[242:243], off
	s_mov_b32 s100, 0xffff3a40
	s_mov_b32 s101, -1
	v_lshl_add_u64 v[242:243], v[74:75], 0, s[100:101]
	global_load_dwordx4 v[236:239], v[242:243], off
	s_mov_b32 s100, 0xffff7c40
	s_mov_b32 s101, -1
	v_lshl_add_u64 v[242:243], v[74:75], 0, s[100:101]
	global_load_dwordx4 v[246:249], v[242:243], off
	s_nop 0
	s_nop 0
	s_waitcnt vmcnt(14)
	v_mov_b32_e32 v86, v4
	s_nop 0
	s_nop 0
	s_waitcnt vmcnt(12)
	v_mov_b32_e32 v87, v16
	v_mov_b32_e32 v16, v5
	v_mov_b32_e32 v84, v6
	s_nop 0
	s_nop 0
	s_waitcnt vmcnt(8)
	v_cndmask_b32_e64 v62, 0, v135, s[2:3]
	v_cndmask_b32_e64 v56, 0, v134, s[2:3]
	v_cndmask_b32_e64 v57, 0, v133, s[2:3]
	v_cndmask_b32_e64 v58, 0, v132, s[2:3]
	s_mov_b32 s100, 0xffffbe40
	s_mov_b32 s101, -1
	v_lshl_add_u64 v[242:243], v[74:75], 0, s[100:101]
	global_load_dwordx4 v[132:135], v[242:243], off
	s_nop 0
	v_mov_b32_e32 v38, v44
	v_mov_b32_e32 v39, v28
	v_mov_b32_e32 v85, v18
	v_mov_b32_e32 v18, v7
	v_mov_b32_e32 v80, v0
	v_mov_b32_e32 v81, v12
	v_mov_b32_e32 v12, v1
	v_mov_b32_e32 v82, v2
	v_mov_b32_e32 v83, v14
	v_mov_b32_e32 v14, v3
	s_nop 0
	s_nop 0
	s_waitcnt vmcnt(8)
	v_cndmask_b32_e64 v59, 0, v136, s[4:5]
	v_cndmask_b32_e64 v63, 0, v139, s[4:5]
	v_cndmask_b32_e64 v55, 0, v137, s[4:5]
	v_lshlrev_b32_e32 v53, 16, v59
	v_lshlrev_b32_e32 v52, 16, v58
	v_pk_mul_f32 v[52:53], v[38:39], v[52:53]
	v_cndmask_b32_e64 v138, 0, v138, s[4:5]
	v_add_f32_e32 v28, v32, v52
	v_add_f32_e32 v61, v28, v53
	v_and_b32_e32 v53, 0xffff0000, v59
	v_and_b32_e32 v52, 0xffff0000, v58
	v_mov_b32_e32 v28, v45
	v_pk_mul_f32 v[44:45], v[28:29], v[52:53]
	v_lshlrev_b32_e32 v53, 16, v55
	v_add_f32_e32 v44, v33, v44
	v_add_f32_e32 v60, v44, v45
	v_lshlrev_b32_e32 v52, 16, v57
	v_mov_b32_e32 v44, v46
	v_mov_b32_e32 v45, v30
	v_pk_mul_f32 v[52:53], v[44:45], v[52:53]
	s_nop 0
	v_add_f32_e32 v30, v34, v52
	v_add_f32_e32 v59, v30, v53
	v_and_b32_e32 v53, 0xffff0000, v55
	v_and_b32_e32 v52, 0xffff0000, v57
	v_mov_b32_e32 v30, v47
	v_pk_mul_f32 v[46:47], v[30:31], v[52:53]
	v_lshlrev_b32_e32 v53, 16, v138
	v_add_f32_e32 v46, v35, v46
	v_add_f32_e32 v58, v46, v47
	v_lshlrev_b32_e32 v52, 16, v56
	v_mov_b32_e32 v46, v8
	v_mov_b32_e32 v47, v20
	v_pk_mul_f32 v[52:53], v[46:47], v[52:53]
	v_mov_b32_e32 v20, v9
	v_add_f32_e32 v8, v24, v52
	v_add_f32_e32 v55, v8, v53
	v_and_b32_e32 v53, 0xffff0000, v138
	s_mov_b32 s100, 0x40
	s_mov_b32 s101, 0
	v_lshl_add_u64 v[242:243], v[74:75], 0, s[100:101]
	global_load_dwordx4 v[136:139], v[242:243], off
	v_and_b32_e32 v52, 0xffff0000, v56
	v_pk_mul_f32 v[8:9], v[20:21], v[52:53]
	v_mov_b32_e32 v56, v10
	v_add_f32_e32 v8, v25, v8
	v_add_f32_e32 v54, v8, v9
	v_lshlrev_b32_e32 v9, 16, v63
	v_lshlrev_b32_e32 v8, 16, v62
	v_mov_b32_e32 v57, v22
	v_pk_mul_f32 v[8:9], v[56:57], v[8:9]
	v_mov_b32_e32 v22, v11
	v_add_f32_e32 v8, v26, v8
	v_add_f32_e32 v53, v8, v9
	v_and_b32_e32 v9, 0xffff0000, v63
	v_and_b32_e32 v8, 0xffff0000, v62
	v_pk_mul_f32 v[8:9], v[22:23], v[8:9]
	s_nop 0
	v_add_f32_e32 v8, v27, v8
	v_add_f32_e32 v52, v8, v9
	v_lshl_add_u64 v[8:9], v[78:79], 0, s[62:63]
	s_nop 0
	s_nop 0
	s_nop 0
	s_waitcnt vmcnt(8)
	v_cndmask_b32_e64 v62, 0, v143, s[8:9]
	v_cndmask_b32_e64 v63, 0, v142, s[8:9]
	v_cndmask_b32_e64 v64, 0, v141, s[8:9]
	v_cndmask_b32_e64 v65, 0, v140, s[8:9]
	s_nop 0
	s_nop 0
	s_nop 0
	s_nop 0
	s_nop 1
	s_waitcnt vmcnt(7)
	v_mov_b32_dpp v166, v162 row_shl:13 row_mask:0xf bank_mask:0xf
	v_mov_b32_dpp v167, v163 row_shl:13 row_mask:0xf bank_mask:0xf
	v_mov_b32_dpp v168, v164 row_shl:13 row_mask:0xf bank_mask:0xf
	v_mov_b32_dpp v169, v165 row_shl:13 row_mask:0xf bank_mask:0xf
	v_mov_b32_dpp v172, v162 row_shl:14 row_mask:0xf bank_mask:0xf
	v_mov_b32_dpp v173, v163 row_shl:14 row_mask:0xf bank_mask:0xf
	v_mov_b32_dpp v174, v164 row_shl:14 row_mask:0xf bank_mask:0xf
	v_mov_b32_dpp v175, v165 row_shl:14 row_mask:0xf bank_mask:0xf
	v_mov_b32_dpp v176, v162 row_shl:15 row_mask:0xf bank_mask:0xf
	v_mov_b32_dpp v177, v163 row_shl:15 row_mask:0xf bank_mask:0xf
	v_mov_b32_dpp v178, v164 row_shl:15 row_mask:0xf bank_mask:0xf
	v_mov_b32_dpp v179, v165 row_shl:15 row_mask:0xf bank_mask:0xf
	v_cndmask_b32_e64 v67, 0, v162, s[10:11]
	v_cndmask_b32_e64 v66, 0, v163, s[10:11]
	v_lshlrev_b32_e32 v9, 16, v67
	v_lshlrev_b32_e32 v8, 16, v65
	v_pk_mul_f32 v[8:9], v[86:87], v[8:9]
	v_cndmask_b32_e64 v164, 0, v164, s[10:11]
	v_add_f32_e32 v4, v61, v8
	v_add_f32_e32 v61, v4, v9
	v_and_b32_e32 v9, 0xffff0000, v67
	v_and_b32_e32 v8, 0xffff0000, v65
	v_pk_mul_f32 v[4:5], v[16:17], v[8:9]
	v_cndmask_b32_e64 v165, 0, v165, s[10:11]
	v_add_f32_e32 v4, v60, v4
	v_add_f32_e32 v8, v4, v5
	v_lshlrev_b32_e32 v5, 16, v66
	v_lshlrev_b32_e32 v4, 16, v64
	v_pk_mul_f32 v[4:5], v[84:85], v[4:5]
	s_nop 0
	v_add_f32_e32 v4, v59, v4
	v_add_f32_e32 v6, v4, v5
	v_and_b32_e32 v5, 0xffff0000, v66
	v_and_b32_e32 v4, 0xffff0000, v64
	v_pk_mul_f32 v[4:5], v[18:19], v[4:5]
	s_nop 0
	v_add_f32_e32 v4, v58, v4
	v_add_f32_e32 v7, v4, v5
	v_lshlrev_b32_e32 v5, 16, v164
	v_lshlrev_b32_e32 v4, 16, v63
	v_pk_mul_f32 v[4:5], v[80:81], v[4:5]
	s_nop 0
	v_add_f32_e32 v0, v55, v4
	v_add_f32_e32 v9, v0, v5
	v_and_b32_e32 v5, 0xffff0000, v164
	v_and_b32_e32 v4, 0xffff0000, v63
	v_pk_mul_f32 v[0:1], v[12:13], v[4:5]
	s_nop 0
	v_add_f32_e32 v0, v54, v0
	v_add_f32_e32 v4, v0, v1
	v_lshlrev_b32_e32 v1, 16, v165
	v_lshlrev_b32_e32 v0, 16, v62
	v_pk_mul_f32 v[0:1], v[82:83], v[0:1]
	v_cvt_pk_bf16_f32 v2, v9, v4
	s_nop 0
	v_add_f32_e32 v0, v53, v0
	v_add_f32_e32 v5, v0, v1
	v_and_b32_e32 v1, 0xffff0000, v165
	s_nop 0
	v_and_b32_e32 v0, 0xffff0000, v62
	v_pk_mul_f32 v[0:1], v[14:15], v[0:1]
	s_nop 0
	v_add_f32_e32 v0, v52, v0
	v_add_f32_e32 v3, v0, v1
	v_cvt_pk_bf16_f32 v0, v61, v8
	v_cvt_pk_bf16_f32 v1, v6, v7
	v_cvt_pk_bf16_f32 v3, v5, v3
	s_mov_b32 s81, 0x35000
	v_add_co_u32_e32 v68, vcc, s81, v74
	s_mov_b32 s81, 0x39000
	s_nop 0
	v_addc_co_u32_e32 v69, vcc, 0, v75, vcc
	s_nop 0
	v_add_co_u32_e32 v70, vcc, s81, v74
	s_mov_b32 s81, 0x3d000
	s_nop 0
	v_addc_co_u32_e32 v71, vcc, 0, v75, vcc
	v_add_co_u32_e32 v72, vcc, s81, v74
	s_mov_b32 s81, 0x42000
	s_nop 0
	v_addc_co_u32_e32 v73, vcc, 0, v75, vcc
	v_add_co_u32_e32 v76, vcc, s81, v74
	s_nop 0
	s_nop 0
	s_nop 1
	s_waitcnt vmcnt(6)
	v_mov_b32_dpp v166, v180 row_shr:3 row_mask:0xf bank_mask:0xf
	v_mov_b32_dpp v167, v181 row_shr:3 row_mask:0xf bank_mask:0xf
	v_mov_b32_dpp v168, v182 row_shr:3 row_mask:0xf bank_mask:0xf
	v_mov_b32_dpp v169, v183 row_shr:3 row_mask:0xf bank_mask:0xf
	v_cndmask_b32_e64 v10, 0, v169, s[12:13]
	v_cndmask_b32_e64 v11, 0, v168, s[12:13]
	v_cndmask_b32_e64 v8, 0, v167, s[12:13]
	v_cndmask_b32_e64 v9, 0, v166, s[12:13]
	s_nop 0
	s_nop 0
	v_addc_co_u32_e32 v77, vcc, 0, v75, vcc
	s_nop 0
	s_nop 0
	s_nop 1
	v_mov_b32_dpp v172, v180 row_shr:2 row_mask:0xf bank_mask:0xf
	v_mov_b32_dpp v173, v181 row_shr:2 row_mask:0xf bank_mask:0xf
	v_mov_b32_dpp v174, v182 row_shr:2 row_mask:0xf bank_mask:0xf
	v_mov_b32_dpp v175, v183 row_shr:2 row_mask:0xf bank_mask:0xf
	v_cndmask_b32_e64 v53, 0, v172, s[14:15]
	v_cndmask_b32_e64 v52, 0, v175, s[14:15]
	v_cndmask_b32_e64 v7, 0, v173, s[14:15]
	v_lshlrev_b32_e32 v5, 16, v53
	v_lshlrev_b32_e32 v4, 16, v9
	v_pk_mul_f32 v[4:5], v[38:39], v[4:5]
	v_cndmask_b32_e64 v174, 0, v174, s[14:15]
	v_add_f32_e32 v4, v32, v4
	v_add_f32_e32 v58, v4, v5
	v_and_b32_e32 v5, 0xffff0000, v53
	v_and_b32_e32 v4, 0xffff0000, v9
	v_pk_mul_f32 v[4:5], v[28:29], v[4:5]
	s_nop 0
	v_add_f32_e32 v4, v33, v4
	v_add_f32_e32 v59, v4, v5
	v_lshlrev_b32_e32 v5, 16, v7
	v_lshlrev_b32_e32 v4, 16, v8
	v_pk_mul_f32 v[4:5], v[44:45], v[4:5]
	s_nop 0
	v_add_f32_e32 v4, v34, v4
	v_add_f32_e32 v9, v4, v5
	v_and_b32_e32 v5, 0xffff0000, v7
	v_and_b32_e32 v4, 0xffff0000, v8
	v_pk_mul_f32 v[4:5], v[30:31], v[4:5]
	s_nop 0
	v_add_f32_e32 v4, v35, v4
	v_add_f32_e32 v8, v4, v5
	v_lshlrev_b32_e32 v5, 16, v174
	v_lshlrev_b32_e32 v4, 16, v11
	v_pk_mul_f32 v[4:5], v[46:47], v[4:5]
	s_nop 0
	v_add_f32_e32 v4, v24, v4
	v_add_f32_e32 v7, v4, v5
	v_and_b32_e32 v5, 0xffff0000, v174
	s_mov_b32 s100, 0x42040
	s_mov_b32 s101, 0
	v_lshl_add_u64 v[242:243], v[74:75], 0, s[100:101]
	global_load_dwordx4 v[172:175], v[242:243], off
	v_and_b32_e32 v4, 0xffff0000, v11
	v_pk_mul_f32 v[4:5], v[20:21], v[4:5]
	v_and_b32_e32 v11, 0xffff0000, v52
	v_add_f32_e32 v4, v25, v4
	v_add_f32_e32 v6, v4, v5
	v_lshlrev_b32_e32 v5, 16, v52
	s_nop 0
	v_lshlrev_b32_e32 v4, 16, v10
	v_pk_mul_f32 v[4:5], v[56:57], v[4:5]
	v_and_b32_e32 v10, 0xffff0000, v10
	v_add_f32_e32 v4, v26, v4
	v_pk_mul_f32 v[10:11], v[22:23], v[10:11]
	v_add_f32_e32 v5, v4, v5
	v_add_f32_e32 v4, v27, v10
	v_add_f32_e32 v4, v4, v11
	s_nop 0
	s_nop 0
	s_nop 1
	v_mov_b32_dpp v176, v180 row_shr:1 row_mask:0xf bank_mask:0xf
	v_mov_b32_dpp v177, v181 row_shr:1 row_mask:0xf bank_mask:0xf
	v_mov_b32_dpp v178, v182 row_shr:1 row_mask:0xf bank_mask:0xf
	v_mov_b32_dpp v179, v183 row_shr:1 row_mask:0xf bank_mask:0xf
	v_cndmask_b32_e64 v60, 0, v179, s[16:17]
	v_cndmask_b32_e64 v61, 0, v178, s[16:17]
	v_cndmask_b32_e64 v62, 0, v177, s[16:17]
	v_cndmask_b32_e64 v63, 0, v176, s[16:17]
	s_nop 0
	s_nop 0
	v_lshlrev_b32_e32 v10, 16, v63
	s_nop 0
	s_nop 0
	s_nop 1
	v_mov_b32_dpp v184, v180 row_shl:13 row_mask:0xf bank_mask:0xf
	v_mov_b32_dpp v185, v181 row_shl:13 row_mask:0xf bank_mask:0xf
	v_mov_b32_dpp v186, v182 row_shl:13 row_mask:0xf bank_mask:0xf
	v_mov_b32_dpp v187, v183 row_shl:13 row_mask:0xf bank_mask:0xf
	v_mov_b32_dpp v212, v180 row_shl:14 row_mask:0xf bank_mask:0xf
	v_mov_b32_dpp v213, v181 row_shl:14 row_mask:0xf bank_mask:0xf
	v_mov_b32_dpp v214, v182 row_shl:14 row_mask:0xf bank_mask:0xf
	v_mov_b32_dpp v215, v183 row_shl:14 row_mask:0xf bank_mask:0xf
	v_mov_b32_dpp v192, v180 row_shl:15 row_mask:0xf bank_mask:0xf
	v_mov_b32_dpp v193, v181 row_shl:15 row_mask:0xf bank_mask:0xf
	v_mov_b32_dpp v194, v182 row_shl:15 row_mask:0xf bank_mask:0xf
	v_mov_b32_dpp v195, v183 row_shl:15 row_mask:0xf bank_mask:0xf
	v_cndmask_b32_e64 v180, 0, v180, s[10:11]
	v_lshlrev_b32_e32 v11, 16, v180
	v_pk_mul_f32 v[10:11], v[86:87], v[10:11]
	v_cndmask_b32_e64 v181, 0, v181, s[10:11]
	v_add_f32_e32 v10, v58, v10
	v_add_f32_e32 v58, v10, v11
	v_and_b32_e32 v11, 0xffff0000, v180
	v_and_b32_e32 v10, 0xffff0000, v63
	v_pk_mul_f32 v[10:11], v[16:17], v[10:11]
	v_cndmask_b32_e64 v182, 0, v182, s[10:11]
	v_add_f32_e32 v10, v59, v10
	v_add_f32_e32 v52, v10, v11
	v_lshlrev_b32_e32 v11, 16, v181
	v_lshlrev_b32_e32 v10, 16, v62
	v_pk_mul_f32 v[10:11], v[84:85], v[10:11]
	v_cndmask_b32_e64 v183, 0, v183, s[10:11]
	v_add_f32_e32 v9, v9, v10
	v_add_f32_e32 v59, v9, v11
	v_and_b32_e32 v11, 0xffff0000, v181
	v_and_b32_e32 v10, 0xffff0000, v62
	v_pk_mul_f32 v[10:11], v[18:19], v[10:11]
	v_lshlrev_b32_e32 v9, 16, v182
	v_add_f32_e32 v8, v8, v10
	v_add_f32_e32 v10, v8, v11
	v_lshlrev_b32_e32 v8, 16, v61
	v_pk_mul_f32 v[8:9], v[80:81], v[8:9]
	s_nop 0
	v_add_f32_e32 v7, v7, v8
	v_add_f32_e32 v11, v7, v9
	v_and_b32_e32 v9, 0xffff0000, v182
	v_and_b32_e32 v8, 0xffff0000, v61
	v_pk_mul_f32 v[8:9], v[12:13], v[8:9]
	v_lshlrev_b32_e32 v7, 16, v183
	v_add_f32_e32 v6, v6, v8
	v_add_f32_e32 v8, v6, v9
	v_lshlrev_b32_e32 v6, 16, v60
	v_pk_mul_f32 v[6:7], v[82:83], v[6:7]
	s_nop 0
	v_add_f32_e32 v5, v5, v6
	v_add_f32_e32 v9, v5, v7
	v_and_b32_e32 v7, 0xffff0000, v183
	s_nop 0
	v_and_b32_e32 v6, 0xffff0000, v60
	v_pk_mul_f32 v[6:7], v[14:15], v[6:7]
	v_cvt_pk_bf16_f32 v5, v59, v10
	s_nop 0
	v_add_f32_e32 v4, v4, v6
	v_add_f32_e32 v7, v4, v7
	v_cvt_pk_bf16_f32 v4, v58, v52
	v_cvt_pk_bf16_f32 v6, v11, v8
	v_cvt_pk_bf16_f32 v7, v9, v7
	s_mov_b32 s81, 0x77000
	v_add_co_u32_e32 v60, vcc, s81, v74
	s_mov_b32 s81, 0x7b000
	s_nop 0
	v_addc_co_u32_e32 v61, vcc, 0, v75, vcc
	s_nop 0
	v_add_co_u32_e32 v62, vcc, s81, v74
	s_mov_b32 s81, 0x7f000
	s_nop 0
	v_addc_co_u32_e32 v63, vcc, 0, v75, vcc
	v_add_co_u32_e32 v64, vcc, s81, v74
	s_mov_b32 s81, 0x84000
	s_nop 0
	v_addc_co_u32_e32 v65, vcc, 0, v75, vcc
	s_nop 0
	v_add_co_u32_e32 v66, vcc, s81, v74
	s_nop 0
	s_nop 0
	s_nop 1
	s_waitcnt vmcnt(6)
	v_mov_b32_dpp v184, v216 row_shr:3 row_mask:0xf bank_mask:0xf
	v_mov_b32_dpp v185, v217 row_shr:3 row_mask:0xf bank_mask:0xf
	v_mov_b32_dpp v186, v218 row_shr:3 row_mask:0xf bank_mask:0xf
	v_mov_b32_dpp v187, v219 row_shr:3 row_mask:0xf bank_mask:0xf
	v_cndmask_b32_e64 v54, 0, v187, s[18:19]
	v_cndmask_b32_e64 v55, 0, v186, s[18:19]
	v_cndmask_b32_e64 v52, 0, v185, s[18:19]
	v_cndmask_b32_e64 v53, 0, v184, s[18:19]
	s_nop 0
	s_nop 0
	v_addc_co_u32_e32 v67, vcc, 0, v75, vcc
	s_nop 0
	s_nop 0
	s_nop 1
	v_mov_b32_dpp v192, v216 row_shr:1 row_mask:0xf bank_mask:0xf
	v_mov_b32_dpp v193, v217 row_shr:1 row_mask:0xf bank_mask:0xf
	v_mov_b32_dpp v194, v218 row_shr:1 row_mask:0xf bank_mask:0xf
	v_mov_b32_dpp v195, v219 row_shr:1 row_mask:0xf bank_mask:0xf
	v_cndmask_b32_e64 v123, 0, v194, s[22:23]
	v_cndmask_b32_e64 v124, 0, v193, s[22:23]
	v_cndmask_b32_e64 v125, 0, v192, s[22:23]
	s_nop 0
	s_nop 0
	s_nop 1
	v_mov_b32_dpp v212, v216 row_shr:2 row_mask:0xf bank_mask:0xf
	v_mov_b32_dpp v213, v217 row_shr:2 row_mask:0xf bank_mask:0xf
	v_mov_b32_dpp v214, v218 row_shr:2 row_mask:0xf bank_mask:0xf
	v_mov_b32_dpp v215, v219 row_shr:2 row_mask:0xf bank_mask:0xf
	v_cndmask_b32_e64 v59, 0, v212, s[20:21]
	v_cndmask_b32_e64 v58, 0, v215, s[20:21]
	v_cndmask_b32_e64 v11, 0, v213, s[20:21]
	v_lshlrev_b32_e32 v9, 16, v59
	v_lshlrev_b32_e32 v8, 16, v53
	v_pk_mul_f32 v[8:9], v[38:39], v[8:9]
	v_cndmask_b32_e64 v214, 0, v214, s[20:21]
	v_add_f32_e32 v8, v32, v8
	v_add_f32_e32 v122, v8, v9
	v_and_b32_e32 v9, 0xffff0000, v59
	v_and_b32_e32 v8, 0xffff0000, v53
	v_pk_mul_f32 v[8:9], v[28:29], v[8:9]
	s_nop 0
	v_add_f32_e32 v8, v33, v8
	v_add_f32_e32 v59, v8, v9
	v_lshlrev_b32_e32 v9, 16, v11
	v_lshlrev_b32_e32 v8, 16, v52
	v_pk_mul_f32 v[8:9], v[44:45], v[8:9]
	s_nop 0
	v_add_f32_e32 v8, v34, v8
	v_add_f32_e32 v53, v8, v9
	v_and_b32_e32 v9, 0xffff0000, v11
	v_and_b32_e32 v8, 0xffff0000, v52
	v_pk_mul_f32 v[8:9], v[30:31], v[8:9]
	s_nop 0
	v_add_f32_e32 v8, v35, v8
	v_add_f32_e32 v52, v8, v9
	v_lshlrev_b32_e32 v9, 16, v214
	v_lshlrev_b32_e32 v8, 16, v55
	v_pk_mul_f32 v[8:9], v[46:47], v[8:9]
	s_nop 0
	v_add_f32_e32 v8, v24, v8
	v_add_f32_e32 v11, v8, v9
	v_and_b32_e32 v9, 0xffff0000, v214
	v_and_b32_e32 v8, 0xffff0000, v55
	v_pk_mul_f32 v[8:9], v[20:21], v[8:9]
	v_and_b32_e32 v55, 0xffff0000, v58
	v_add_f32_e32 v8, v25, v8
	v_add_f32_e32 v10, v8, v9
	v_lshlrev_b32_e32 v9, 16, v58
	v_cndmask_b32_e64 v58, 0, v195, s[22:23]
	s_mov_b32 s100, 0x84040
	s_mov_b32 s101, 0
	v_lshl_add_u64 v[242:243], v[74:75], 0, s[100:101]
	global_load_dwordx4 v[192:195], v[242:243], off
	s_nop 0
	s_nop 0
	v_lshlrev_b32_e32 v8, 16, v54
	v_pk_mul_f32 v[8:9], v[56:57], v[8:9]
	v_and_b32_e32 v54, 0xffff0000, v54
	v_add_f32_e32 v8, v26, v8
	v_pk_mul_f32 v[54:55], v[22:23], v[54:55]
	v_add_f32_e32 v9, v8, v9
	v_add_f32_e32 v8, v27, v54
	v_add_f32_e32 v8, v8, v55
	v_lshlrev_b32_e32 v54, 16, v125
	s_nop 0
	s_nop 0
	s_nop 1
	v_mov_b32_dpp v220, v216 row_shl:13 row_mask:0xf bank_mask:0xf
	v_mov_b32_dpp v221, v217 row_shl:13 row_mask:0xf bank_mask:0xf
	v_mov_b32_dpp v222, v218 row_shl:13 row_mask:0xf bank_mask:0xf
	v_mov_b32_dpp v223, v219 row_shl:13 row_mask:0xf bank_mask:0xf
	v_mov_b32_dpp v224, v216 row_shl:14 row_mask:0xf bank_mask:0xf
	v_mov_b32_dpp v225, v217 row_shl:14 row_mask:0xf bank_mask:0xf
	v_mov_b32_dpp v226, v218 row_shl:14 row_mask:0xf bank_mask:0xf
	v_mov_b32_dpp v227, v219 row_shl:14 row_mask:0xf bank_mask:0xf
	v_mov_b32_dpp v228, v216 row_shl:15 row_mask:0xf bank_mask:0xf
	v_mov_b32_dpp v229, v217 row_shl:15 row_mask:0xf bank_mask:0xf
	v_mov_b32_dpp v230, v218 row_shl:15 row_mask:0xf bank_mask:0xf
	v_mov_b32_dpp v231, v219 row_shl:15 row_mask:0xf bank_mask:0xf
	v_cndmask_b32_e64 v216, 0, v216, s[10:11]
	v_lshlrev_b32_e32 v55, 16, v216
	v_pk_mul_f32 v[54:55], v[86:87], v[54:55]
	v_cndmask_b32_e64 v217, 0, v217, s[10:11]
	v_add_f32_e32 v54, v122, v54
	v_add_f32_e32 v122, v54, v55
	v_and_b32_e32 v55, 0xffff0000, v216
	v_and_b32_e32 v54, 0xffff0000, v125
	v_pk_mul_f32 v[54:55], v[16:17], v[54:55]
	v_cndmask_b32_e64 v218, 0, v218, s[10:11]
	v_add_f32_e32 v54, v59, v54
	v_add_f32_e32 v59, v54, v55
	v_lshlrev_b32_e32 v55, 16, v217
	v_lshlrev_b32_e32 v54, 16, v124
	v_pk_mul_f32 v[54:55], v[84:85], v[54:55]
	v_cndmask_b32_e64 v219, 0, v219, s[10:11]
	v_add_f32_e32 v53, v53, v54
	v_add_f32_e32 v118, v53, v55
	v_and_b32_e32 v55, 0xffff0000, v217
	v_and_b32_e32 v54, 0xffff0000, v124
	v_pk_mul_f32 v[54:55], v[18:19], v[54:55]
	v_lshlrev_b32_e32 v53, 16, v218
	v_add_f32_e32 v52, v52, v54
	v_add_f32_e32 v54, v52, v55
	v_lshlrev_b32_e32 v52, 16, v123
	v_pk_mul_f32 v[52:53], v[80:81], v[52:53]
	s_nop 0
	v_add_f32_e32 v11, v11, v52
	v_add_f32_e32 v55, v11, v53
	v_and_b32_e32 v53, 0xffff0000, v218
	v_and_b32_e32 v52, 0xffff0000, v123
	v_pk_mul_f32 v[52:53], v[12:13], v[52:53]
	v_lshlrev_b32_e32 v11, 16, v219
	v_add_f32_e32 v10, v10, v52
	v_add_f32_e32 v52, v10, v53
	v_lshlrev_b32_e32 v10, 16, v58
	v_pk_mul_f32 v[10:11], v[82:83], v[10:11]
	s_nop 0
	v_add_f32_e32 v9, v9, v10
	v_add_f32_e32 v53, v9, v11
	v_and_b32_e32 v11, 0xffff0000, v219
	s_nop 0
	v_and_b32_e32 v10, 0xffff0000, v58
	v_pk_mul_f32 v[10:11], v[14:15], v[10:11]
	v_cvt_pk_bf16_f32 v9, v118, v54
	s_nop 0
	v_add_f32_e32 v8, v8, v10
	v_add_f32_e32 v11, v8, v11
	v_cvt_pk_bf16_f32 v8, v122, v59
	v_cvt_pk_bf16_f32 v10, v55, v52
	v_cvt_pk_bf16_f32 v11, v53, v11
	s_mov_b32 s81, 0xb9000
	v_add_co_u32_e32 v52, vcc, s81, v74
	s_mov_b32 s81, 0xbd000
	s_nop 0
	v_addc_co_u32_e32 v53, vcc, 0, v75, vcc
	s_nop 0
	v_add_co_u32_e32 v54, vcc, s81, v74
	s_mov_b32 s81, 0xc1000
	s_nop 0
	v_addc_co_u32_e32 v55, vcc, 0, v75, vcc
	s_nop 0
	s_nop 0
	s_nop 1
	s_waitcnt vmcnt(6)
	v_mov_b32_dpp v220, v232 row_shr:3 row_mask:0xf bank_mask:0xf
	v_mov_b32_dpp v221, v233 row_shr:3 row_mask:0xf bank_mask:0xf
	v_mov_b32_dpp v222, v234 row_shr:3 row_mask:0xf bank_mask:0xf
	v_mov_b32_dpp v223, v235 row_shr:3 row_mask:0xf bank_mask:0xf
	v_cndmask_b32_e64 v122, 0, v223, s[0:1]
	v_cndmask_b32_e64 v123, 0, v222, s[0:1]
	v_cndmask_b32_e64 v124, 0, v221, s[0:1]
	v_cndmask_b32_e64 v125, 0, v220, s[0:1]
	s_nop 0
	s_nop 0
	v_lshlrev_b32_e32 v58, 16, v125
	s_nop 0
	s_nop 0
	s_nop 1
	v_mov_b32_dpp v224, v232 row_shr:2 row_mask:0xf bank_mask:0xf
	v_mov_b32_dpp v225, v233 row_shr:2 row_mask:0xf bank_mask:0xf
	v_mov_b32_dpp v226, v234 row_shr:2 row_mask:0xf bank_mask:0xf
	v_mov_b32_dpp v227, v235 row_shr:2 row_mask:0xf bank_mask:0xf
	v_cndmask_b32_e64 v224, 0, v224, s[24:25]
	v_lshlrev_b32_e32 v59, 16, v224
	v_pk_mul_f32 v[38:39], v[38:39], v[58:59]
	v_cndmask_b32_e64 v225, 0, v225, s[24:25]
	v_add_f32_e32 v32, v32, v38
	v_add_f32_e32 v126, v32, v39
	v_and_b32_e32 v39, 0xffff0000, v224
	v_and_b32_e32 v38, 0xffff0000, v125
	v_pk_mul_f32 v[28:29], v[28:29], v[38:39]
	v_cndmask_b32_e64 v226, 0, v226, s[24:25]
	v_add_f32_e32 v28, v33, v28
	v_add_f32_e32 v33, v28, v29
	v_lshlrev_b32_e32 v29, 16, v225
	v_lshlrev_b32_e32 v28, 16, v124
	v_pk_mul_f32 v[28:29], v[44:45], v[28:29]
	v_cndmask_b32_e64 v227, 0, v227, s[24:25]
	v_add_f32_e32 v28, v34, v28
	v_add_f32_e32 v32, v28, v29
	v_and_b32_e32 v29, 0xffff0000, v225
	v_and_b32_e32 v28, 0xffff0000, v124
	v_pk_mul_f32 v[28:29], v[30:31], v[28:29]
	v_lshlrev_b32_e32 v31, 16, v226
	v_lshlrev_b32_e32 v30, 16, v123
	v_pk_mul_f32 v[30:31], v[46:47], v[30:31]
	v_add_f32_e32 v28, v35, v28
	v_add_f32_e32 v24, v24, v30
	v_add_f32_e32 v29, v28, v29
	v_add_f32_e32 v28, v24, v31
	v_and_b32_e32 v31, 0xffff0000, v226
	v_and_b32_e32 v30, 0xffff0000, v123
	v_pk_mul_f32 v[20:21], v[20:21], v[30:31]
	v_and_b32_e32 v31, 0xffff0000, v227
	v_add_f32_e32 v20, v25, v20
	v_add_f32_e32 v24, v20, v21
	v_lshlrev_b32_e32 v21, 16, v227
	s_mov_b32 s100, 0xc6040
	s_mov_b32 s101, 0
	v_lshl_add_u64 v[242:243], v[74:75], 0, s[100:101]
	global_load_dwordx4 v[224:227], v[242:243], off
	v_lshlrev_b32_e32 v20, 16, v122
	v_pk_mul_f32 v[20:21], v[56:57], v[20:21]
	v_add_co_u32_e32 v56, vcc, s81, v74
	s_mov_b32 s81, 0xc6000
	s_nop 0
	v_addc_co_u32_e32 v57, vcc, 0, v75, vcc
	s_nop 0
	v_and_b32_e32 v30, 0xffff0000, v122
	v_add_co_u32_e32 v58, vcc, s81, v74
	v_add_f32_e32 v20, v26, v20
	v_pk_mul_f32 v[22:23], v[22:23], v[30:31]
	v_addc_co_u32_e32 v59, vcc, 0, v75, vcc
	v_add_f32_e32 v21, v20, v21
	v_add_f32_e32 v20, v27, v22
	v_add_f32_e32 v20, v20, v23
	s_nop 0
	s_nop 0
	s_nop 1
	v_mov_b32_dpp v228, v232 row_shr:1 row_mask:0xf bank_mask:0xf
	v_mov_b32_dpp v229, v233 row_shr:1 row_mask:0xf bank_mask:0xf
	v_mov_b32_dpp v230, v234 row_shr:1 row_mask:0xf bank_mask:0xf
	v_mov_b32_dpp v231, v235 row_shr:1 row_mask:0xf bank_mask:0xf
	v_cndmask_b32_e64 v25, 0, v231, s[26:27]
	v_cndmask_b32_e64 v26, 0, v230, s[26:27]
	v_cndmask_b32_e64 v27, 0, v229, s[26:27]
	v_cndmask_b32_e64 v30, 0, v228, s[26:27]
	s_nop 0
	v_lshlrev_b32_e32 v22, 16, v30
	s_nop 0
	s_nop 0
	v_cndmask_b32_e64 v38, 0, v232, s[10:11]
	v_lshlrev_b32_e32 v23, 16, v38
	v_pk_mul_f32 v[22:23], v[86:87], v[22:23]
	v_cndmask_b32_e64 v35, 0, v233, s[10:11]
	v_add_f32_e32 v22, v126, v22
	v_add_f32_e32 v39, v22, v23
	v_and_b32_e32 v23, 0xffff0000, v38
	v_and_b32_e32 v22, 0xffff0000, v30
	v_pk_mul_f32 v[16:17], v[16:17], v[22:23]
	v_cndmask_b32_e64 v34, 0, v234, s[10:11]
	v_add_f32_e32 v16, v33, v16
	v_add_f32_e32 v22, v16, v17
	v_lshlrev_b32_e32 v17, 16, v35
	v_lshlrev_b32_e32 v16, 16, v27
	v_pk_mul_f32 v[16:17], v[84:85], v[16:17]
	v_cndmask_b32_e64 v31, 0, v235, s[10:11]
	v_add_f32_e32 v16, v32, v16
	v_add_f32_e32 v23, v16, v17
	v_and_b32_e32 v17, 0xffff0000, v35
	v_and_b32_e32 v16, 0xffff0000, v27
	v_pk_mul_f32 v[16:17], v[18:19], v[16:17]
	s_nop 0
	v_add_f32_e32 v16, v29, v16
	v_add_f32_e32 v18, v16, v17
	v_lshlrev_b32_e32 v17, 16, v34
	v_lshlrev_b32_e32 v16, 16, v26
	v_pk_mul_f32 v[16:17], v[80:81], v[16:17]
	s_nop 0
	v_add_f32_e32 v16, v28, v16
	v_add_f32_e32 v19, v16, v17
	v_and_b32_e32 v17, 0xffff0000, v34
	v_and_b32_e32 v16, 0xffff0000, v26
	v_pk_mul_f32 v[12:13], v[12:13], v[16:17]
	s_nop 0
	v_add_f32_e32 v12, v24, v12
	v_add_f32_e32 v16, v12, v13
	v_lshlrev_b32_e32 v13, 16, v31
	v_lshlrev_b32_e32 v12, 16, v25
	v_pk_mul_f32 v[12:13], v[82:83], v[12:13]
	s_nop 0
	v_add_f32_e32 v12, v21, v12
	v_add_f32_e32 v17, v12, v13
	v_and_b32_e32 v13, 0xffff0000, v31
	v_and_b32_e32 v12, 0xffff0000, v25
	v_pk_mul_f32 v[12:13], v[14:15], v[12:13]
	v_cvt_pk_bf16_f32 v14, v19, v16
	s_nop 0
	v_add_f32_e32 v12, v20, v12
	v_add_f32_e32 v15, v12, v13
	v_cvt_pk_bf16_f32 v12, v39, v22
	v_cvt_pk_bf16_f32 v13, v23, v18
	v_cvt_pk_bf16_f32 v15, v17, v15
	global_load_dwordx4 v[24:27], v144, s[84:85] offset:144
	global_load_dwordx4 v[80:83], v144, s[84:85] offset:128
	s_mov_b64 s[84:85], 0x1080
	v_lshl_add_u64 v[16:17], v[40:41], 0, s[84:85]
	s_mov_b64 s[84:85], 0x2080
	global_load_dwordx4 v[44:47], v[36:37], off offset:128
	s_nop 0
	global_load_dwordx4 v[36:39], v[16:17], off offset:16
	v_lshl_add_u64 v[16:17], v[40:41], 0, s[84:85]
	s_mov_b64 s[84:85], 0x3080
	v_lshl_add_u64 v[120:121], v[78:79], 0, 64
	v_lshl_add_u64 v[28:29], v[40:41], 0, s[84:85]
	v_lshl_add_u64 v[78:79], v[120:121], 0, s[58:59]
	global_load_dwordx4 v[20:23], v[42:43], off offset:128
	s_nop 0
	global_load_dwordx4 v[16:19], v[16:17], off offset:16
	s_nop 0
	global_load_dwordx4 v[32:35], v[48:49], off offset:128
	s_nop 0
	global_load_dwordx4 v[28:31], v[28:29], off offset:16
	s_nop 0
	global_load_dwordx4 v[40:43], v[50:51], off offset:144
	s_nop 0
	global_load_dwordx4 v[48:51], v[50:51], off offset:128
	s_ashr_i32 s81, s80, 31
	s_nop 0
	v_lshl_add_u64 v[78:79], v[120:121], 0, s[60:61]
	s_nop 0
	s_nop 0
	s_waitcnt vmcnt(16)
	v_cndmask_b32_e64 v122, 0, v239, s[2:3]
	v_cndmask_b32_e64 v123, 0, v238, s[2:3]
	v_cndmask_b32_e64 v124, 0, v237, s[2:3]
	v_cndmask_b32_e64 v118, 0, v236, s[2:3]
	s_nop 0
	s_nop 0
	s_waitcnt vmcnt(8)
	v_mov_b32_e32 v78, v80
	s_nop 0
	s_waitcnt vmcnt(7)
	v_mov_b32_e32 v79, v44
	s_nop 0
	v_cndmask_b32_e64 v126, 0, v249, s[4:5]
	v_cndmask_b32_e64 v87, 0, v246, s[4:5]
	v_cndmask_b32_e64 v127, 0, v248, s[4:5]
	v_cndmask_b32_e64 v86, 0, v247, s[4:5]
	v_lshlrev_b32_e32 v85, 16, v87
	v_lshlrev_b32_e32 v84, 16, v118
	v_pk_mul_f32 v[84:85], v[78:79], v[84:85]
	s_nop 0
	s_nop 0
	s_waitcnt vmcnt(0)
	v_add_f32_e32 v44, v48, v84
	v_add_f32_e32 v119, v44, v85
	v_and_b32_e32 v85, 0xffff0000, v87
	v_and_b32_e32 v84, 0xffff0000, v118
	v_mov_b32_e32 v44, v81
	v_pk_mul_f32 v[80:81], v[44:45], v[84:85]
	v_lshlrev_b32_e32 v85, 16, v86
	v_add_f32_e32 v80, v49, v80
	v_add_f32_e32 v118, v80, v81
	v_lshlrev_b32_e32 v84, 16, v124
	v_mov_b32_e32 v80, v82
	v_mov_b32_e32 v81, v46
	v_pk_mul_f32 v[84:85], v[80:81], v[84:85]
	s_nop 0
	v_add_f32_e32 v46, v50, v84
	v_add_f32_e32 v87, v46, v85
	v_and_b32_e32 v85, 0xffff0000, v86
	v_and_b32_e32 v84, 0xffff0000, v124
	v_mov_b32_e32 v46, v83
	v_pk_mul_f32 v[82:83], v[46:47], v[84:85]
	v_lshlrev_b32_e32 v85, 16, v127
	v_add_f32_e32 v82, v51, v82
	v_add_f32_e32 v86, v82, v83
	v_lshlrev_b32_e32 v84, 16, v123
	v_mov_b32_e32 v82, v24
	v_mov_b32_e32 v83, v36
	v_pk_mul_f32 v[84:85], v[82:83], v[84:85]
	v_mov_b32_e32 v36, v25
	v_add_f32_e32 v24, v40, v84
	v_add_f32_e32 v125, v24, v85
	v_and_b32_e32 v85, 0xffff0000, v127
	v_and_b32_e32 v84, 0xffff0000, v123
	v_pk_mul_f32 v[24:25], v[36:37], v[84:85]
	v_mov_b32_e32 v84, v26
	v_add_f32_e32 v24, v41, v24
	v_add_f32_e32 v124, v24, v25
	v_lshlrev_b32_e32 v25, 16, v126
	v_lshlrev_b32_e32 v24, 16, v122
	v_mov_b32_e32 v85, v38
	v_pk_mul_f32 v[24:25], v[84:85], v[24:25]
	v_mov_b32_e32 v38, v27
	v_add_f32_e32 v24, v42, v24
	v_add_f32_e32 v123, v24, v25
	v_and_b32_e32 v25, 0xffff0000, v126
	v_and_b32_e32 v24, 0xffff0000, v122
	v_pk_mul_f32 v[24:25], v[38:39], v[24:25]
	s_nop 0
	v_add_f32_e32 v24, v43, v24
	v_add_f32_e32 v122, v24, v25
	v_lshl_add_u64 v[24:25], v[120:121], 0, s[62:63]
	s_nop 0
	v_mov_b32_e32 v120, v20
	v_mov_b32_e32 v121, v32
	v_mov_b32_e32 v32, v21
	s_nop 0
	v_cndmask_b32_e64 v126, 0, v135, s[8:9]
	v_cndmask_b32_e64 v127, 0, v134, s[8:9]
	v_cndmask_b32_e64 v128, 0, v133, s[8:9]
	v_cndmask_b32_e64 v129, 0, v132, s[8:9]
	s_nop 0
	s_nop 0
	v_cndmask_b32_e64 v75, 0, v136, s[10:11]
	v_cndmask_b32_e64 v74, 0, v137, s[10:11]
	v_lshlrev_b32_e32 v25, 16, v75
	v_lshlrev_b32_e32 v24, 16, v129
	v_pk_mul_f32 v[24:25], v[120:121], v[24:25]
	v_cndmask_b32_e64 v138, 0, v138, s[10:11]
	v_add_f32_e32 v20, v119, v24
	v_add_f32_e32 v130, v20, v25
	v_and_b32_e32 v25, 0xffff0000, v75
	v_and_b32_e32 v24, 0xffff0000, v129
	v_pk_mul_f32 v[20:21], v[32:33], v[24:25]
	v_mov_b32_e32 v119, v34
	v_add_f32_e32 v20, v118, v20
	v_add_f32_e32 v24, v20, v21
	v_lshlrev_b32_e32 v21, 16, v74
	v_lshlrev_b32_e32 v20, 16, v128
	v_mov_b32_e32 v118, v22
	v_pk_mul_f32 v[20:21], v[118:119], v[20:21]
	v_mov_b32_e32 v34, v23
	v_add_f32_e32 v20, v87, v20
	v_add_f32_e32 v22, v20, v21
	v_and_b32_e32 v21, 0xffff0000, v74
	v_and_b32_e32 v20, 0xffff0000, v128
	v_pk_mul_f32 v[20:21], v[34:35], v[20:21]
	v_mov_b32_e32 v87, v28
	v_add_f32_e32 v20, v86, v20
	v_add_f32_e32 v23, v20, v21
	v_lshlrev_b32_e32 v21, 16, v138
	v_lshlrev_b32_e32 v20, 16, v127
	v_mov_b32_e32 v86, v16
	v_pk_mul_f32 v[20:21], v[86:87], v[20:21]
	v_mov_b32_e32 v28, v17
	v_add_f32_e32 v16, v125, v20
	v_add_f32_e32 v25, v16, v21
	v_and_b32_e32 v21, 0xffff0000, v138
	v_and_b32_e32 v20, 0xffff0000, v127
	v_pk_mul_f32 v[16:17], v[28:29], v[20:21]
	v_cndmask_b32_e64 v139, 0, v139, s[10:11]
	v_add_f32_e32 v16, v124, v16
	v_add_f32_e32 v20, v16, v17
	v_lshlrev_b32_e32 v17, 16, v139
	v_lshlrev_b32_e32 v16, 16, v126
	v_mov_b32_e32 v74, v18
	v_mov_b32_e32 v75, v30
	v_pk_mul_f32 v[16:17], v[74:75], v[16:17]
	v_mov_b32_e32 v30, v19
	v_add_f32_e32 v16, v123, v16
	v_add_f32_e32 v21, v16, v17
	v_and_b32_e32 v17, 0xffff0000, v139
	v_and_b32_e32 v16, 0xffff0000, v126
	v_pk_mul_f32 v[16:17], v[30:31], v[16:17]
	v_cvt_pk_bf16_f32 v18, v25, v20
	s_nop 0
	v_add_f32_e32 v16, v122, v16
	v_add_f32_e32 v19, v16, v17
	v_cvt_pk_bf16_f32 v16, v130, v24
	v_cvt_pk_bf16_f32 v17, v22, v23
	v_cvt_pk_bf16_f32 v19, v21, v19
	s_nop 0
	s_nop 0
	s_nop 1
	v_mov_b32_dpp v140, v136 row_shl:13 row_mask:0xf bank_mask:0xf
	v_mov_b32_dpp v141, v137 row_shl:13 row_mask:0xf bank_mask:0xf
	v_mov_b32_dpp v142, v138 row_shl:13 row_mask:0xf bank_mask:0xf
	v_mov_b32_dpp v143, v139 row_shl:13 row_mask:0xf bank_mask:0xf
	v_mov_b32_dpp v140, v172 row_shr:3 row_mask:0xf bank_mask:0xf
	v_mov_b32_dpp v141, v173 row_shr:3 row_mask:0xf bank_mask:0xf
	v_mov_b32_dpp v142, v174 row_shr:3 row_mask:0xf bank_mask:0xf
	v_mov_b32_dpp v143, v175 row_shr:3 row_mask:0xf bank_mask:0xf
	v_cndmask_b32_e64 v24, 0, v143, s[12:13]
	v_cndmask_b32_e64 v25, 0, v142, s[12:13]
	v_cndmask_b32_e64 v26, 0, v141, s[12:13]
	v_cndmask_b32_e64 v27, 0, v140, s[12:13]
	s_nop 0
	s_nop 0
	s_nop 1
	v_mov_b32_dpp v162, v136 row_shl:14 row_mask:0xf bank_mask:0xf
	v_mov_b32_dpp v163, v137 row_shl:14 row_mask:0xf bank_mask:0xf
	v_mov_b32_dpp v164, v138 row_shl:14 row_mask:0xf bank_mask:0xf
	v_mov_b32_dpp v165, v139 row_shl:14 row_mask:0xf bank_mask:0xf
	v_mov_b32_dpp v162, v172 row_shr:2 row_mask:0xf bank_mask:0xf
	v_mov_b32_dpp v163, v173 row_shr:2 row_mask:0xf bank_mask:0xf
	v_mov_b32_dpp v164, v174 row_shr:2 row_mask:0xf bank_mask:0xf
	v_mov_b32_dpp v165, v175 row_shr:2 row_mask:0xf bank_mask:0xf
	v_cndmask_b32_e64 v69, 0, v162, s[14:15]
	v_cndmask_b32_e64 v68, 0, v163, s[14:15]
	v_lshlrev_b32_e32 v21, 16, v69
	v_lshlrev_b32_e32 v20, 16, v27
	v_pk_mul_f32 v[20:21], v[78:79], v[20:21]
	v_cndmask_b32_e64 v164, 0, v164, s[14:15]
	v_add_f32_e32 v20, v48, v20
	v_add_f32_e32 v70, v20, v21
	v_and_b32_e32 v21, 0xffff0000, v69
	v_and_b32_e32 v20, 0xffff0000, v27
	v_pk_mul_f32 v[20:21], v[44:45], v[20:21]
	v_cndmask_b32_e64 v165, 0, v165, s[14:15]
	v_add_f32_e32 v20, v49, v20
	v_add_f32_e32 v69, v20, v21
	v_lshlrev_b32_e32 v21, 16, v68
	v_lshlrev_b32_e32 v20, 16, v26
	v_pk_mul_f32 v[20:21], v[80:81], v[20:21]
	s_nop 0
	v_add_f32_e32 v20, v50, v20
	v_add_f32_e32 v71, v20, v21
	v_and_b32_e32 v21, 0xffff0000, v68
	v_and_b32_e32 v20, 0xffff0000, v26
	v_pk_mul_f32 v[20:21], v[46:47], v[20:21]
	s_nop 0
	v_add_f32_e32 v20, v51, v20
	v_add_f32_e32 v68, v20, v21
	v_lshlrev_b32_e32 v21, 16, v164
	v_lshlrev_b32_e32 v20, 16, v25
	v_pk_mul_f32 v[20:21], v[82:83], v[20:21]
	s_nop 0
	v_add_f32_e32 v20, v40, v20
	v_add_f32_e32 v122, v20, v21
	v_and_b32_e32 v21, 0xffff0000, v164
	v_and_b32_e32 v20, 0xffff0000, v25
	v_pk_mul_f32 v[20:21], v[36:37], v[20:21]
	v_and_b32_e32 v25, 0xffff0000, v165
	v_add_f32_e32 v20, v41, v20
	v_add_f32_e32 v22, v20, v21
	v_lshlrev_b32_e32 v21, 16, v165
	v_lshlrev_b32_e32 v20, 16, v24
	v_pk_mul_f32 v[20:21], v[84:85], v[20:21]
	v_and_b32_e32 v24, 0xffff0000, v24
	v_add_f32_e32 v20, v42, v20
	v_pk_mul_f32 v[24:25], v[38:39], v[24:25]
	v_add_f32_e32 v21, v20, v21
	v_add_f32_e32 v20, v43, v24
	v_add_f32_e32 v20, v20, v25
	s_nop 0
	s_nop 0
	s_nop 1
	v_mov_b32_dpp v166, v136 row_shl:15 row_mask:0xf bank_mask:0xf
	v_mov_b32_dpp v167, v137 row_shl:15 row_mask:0xf bank_mask:0xf
	v_mov_b32_dpp v168, v138 row_shl:15 row_mask:0xf bank_mask:0xf
	v_mov_b32_dpp v169, v139 row_shl:15 row_mask:0xf bank_mask:0xf
	v_mov_b32_dpp v166, v172 row_shr:1 row_mask:0xf bank_mask:0xf
	v_mov_b32_dpp v167, v173 row_shr:1 row_mask:0xf bank_mask:0xf
	v_mov_b32_dpp v168, v174 row_shr:1 row_mask:0xf bank_mask:0xf
	v_mov_b32_dpp v169, v175 row_shr:1 row_mask:0xf bank_mask:0xf
	v_cndmask_b32_e64 v72, 0, v169, s[16:17]
	v_cndmask_b32_e64 v23, 0, v168, s[16:17]
	v_cndmask_b32_e64 v73, 0, v167, s[16:17]
	v_cndmask_b32_e64 v123, 0, v166, s[16:17]
	s_nop 0
	s_nop 0
	v_cndmask_b32_e64 v77, 0, v172, s[10:11]
	v_cndmask_b32_e64 v76, 0, v173, s[10:11]
	v_lshlrev_b32_e32 v25, 16, v77
	v_lshlrev_b32_e32 v24, 16, v123
	v_pk_mul_f32 v[24:25], v[120:121], v[24:25]
	v_cndmask_b32_e64 v174, 0, v174, s[10:11]
	v_add_f32_e32 v24, v70, v24
	v_add_f32_e32 v70, v24, v25
	v_and_b32_e32 v25, 0xffff0000, v77
	v_and_b32_e32 v24, 0xffff0000, v123
	v_pk_mul_f32 v[24:25], v[32:33], v[24:25]
	v_cndmask_b32_e64 v175, 0, v175, s[10:11]
	v_add_f32_e32 v24, v69, v24
	v_add_f32_e32 v69, v24, v25
	v_lshlrev_b32_e32 v25, 16, v76
	v_lshlrev_b32_e32 v24, 16, v73
	v_pk_mul_f32 v[24:25], v[118:119], v[24:25]
	s_nop 0
	v_add_f32_e32 v24, v71, v24
	v_add_f32_e32 v71, v24, v25
	v_and_b32_e32 v25, 0xffff0000, v76
	v_and_b32_e32 v24, 0xffff0000, v73
	v_pk_mul_f32 v[24:25], v[34:35], v[24:25]
	s_nop 0
	v_add_f32_e32 v24, v68, v24
	v_add_f32_e32 v68, v24, v25
	v_lshlrev_b32_e32 v25, 16, v174
	v_lshlrev_b32_e32 v24, 16, v23
	v_pk_mul_f32 v[24:25], v[86:87], v[24:25]
	s_nop 0
	v_add_f32_e32 v24, v122, v24
	v_add_f32_e32 v73, v24, v25
	v_and_b32_e32 v25, 0xffff0000, v174
	v_and_b32_e32 v24, 0xffff0000, v23
	v_pk_mul_f32 v[24:25], v[28:29], v[24:25]
	v_lshlrev_b32_e32 v23, 16, v175
	v_add_f32_e32 v22, v22, v24
	v_add_f32_e32 v24, v22, v25
	v_lshlrev_b32_e32 v22, 16, v72
	v_pk_mul_f32 v[22:23], v[74:75], v[22:23]
	s_nop 0
	v_add_f32_e32 v21, v21, v22
	v_add_f32_e32 v25, v21, v23
	v_and_b32_e32 v23, 0xffff0000, v175
	v_and_b32_e32 v22, 0xffff0000, v72
	v_pk_mul_f32 v[22:23], v[30:31], v[22:23]
	v_cvt_pk_bf16_f32 v21, v71, v68
	s_nop 0
	v_add_f32_e32 v20, v20, v22
	v_add_f32_e32 v23, v20, v23
	v_cvt_pk_bf16_f32 v20, v70, v69
	v_cvt_pk_bf16_f32 v22, v73, v24
	v_cvt_pk_bf16_f32 v23, v25, v23
	s_nop 0
	s_nop 0
	s_nop 1
	v_mov_b32_dpp v176, v172 row_shl:13 row_mask:0xf bank_mask:0xf
	v_mov_b32_dpp v177, v173 row_shl:13 row_mask:0xf bank_mask:0xf
	v_mov_b32_dpp v178, v174 row_shl:13 row_mask:0xf bank_mask:0xf
	v_mov_b32_dpp v179, v175 row_shl:13 row_mask:0xf bank_mask:0xf
	v_mov_b32_dpp v176, v192 row_shr:3 row_mask:0xf bank_mask:0xf
	v_mov_b32_dpp v177, v193 row_shr:3 row_mask:0xf bank_mask:0xf
	v_mov_b32_dpp v178, v194 row_shr:3 row_mask:0xf bank_mask:0xf
	v_mov_b32_dpp v179, v195 row_shr:3 row_mask:0xf bank_mask:0xf
	v_cndmask_b32_e64 v60, 0, v179, s[18:19]
	v_cndmask_b32_e64 v61, 0, v178, s[18:19]
	v_cndmask_b32_e64 v68, 0, v177, s[18:19]
	v_cndmask_b32_e64 v69, 0, v176, s[18:19]
	s_nop 0
	s_nop 0
	s_nop 1
	v_mov_b32_dpp v180, v172 row_shl:14 row_mask:0xf bank_mask:0xf
	v_mov_b32_dpp v181, v173 row_shl:14 row_mask:0xf bank_mask:0xf
	v_mov_b32_dpp v182, v174 row_shl:14 row_mask:0xf bank_mask:0xf
	v_mov_b32_dpp v183, v175 row_shl:14 row_mask:0xf bank_mask:0xf
	v_mov_b32_dpp v180, v192 row_shr:2 row_mask:0xf bank_mask:0xf
	v_mov_b32_dpp v181, v193 row_shr:2 row_mask:0xf bank_mask:0xf
	v_mov_b32_dpp v182, v194 row_shr:2 row_mask:0xf bank_mask:0xf
	v_mov_b32_dpp v183, v195 row_shr:2 row_mask:0xf bank_mask:0xf
	v_cndmask_b32_e64 v63, 0, v180, s[20:21]
	v_cndmask_b32_e64 v62, 0, v181, s[20:21]
	v_lshlrev_b32_e32 v25, 16, v63
	v_lshlrev_b32_e32 v24, 16, v69
	v_pk_mul_f32 v[24:25], v[78:79], v[24:25]
	v_cndmask_b32_e64 v182, 0, v182, s[20:21]
	v_add_f32_e32 v24, v48, v24
	v_add_f32_e32 v70, v24, v25
	v_and_b32_e32 v25, 0xffff0000, v63
	v_and_b32_e32 v24, 0xffff0000, v69
	v_pk_mul_f32 v[24:25], v[44:45], v[24:25]
	v_cndmask_b32_e64 v183, 0, v183, s[20:21]
	v_add_f32_e32 v24, v49, v24
	v_add_f32_e32 v69, v24, v25
	v_lshlrev_b32_e32 v25, 16, v62
	v_lshlrev_b32_e32 v24, 16, v68
	v_pk_mul_f32 v[24:25], v[80:81], v[24:25]
	s_nop 0
	v_add_f32_e32 v24, v50, v24
	v_add_f32_e32 v71, v24, v25
	v_and_b32_e32 v25, 0xffff0000, v62
	v_and_b32_e32 v24, 0xffff0000, v68
	v_pk_mul_f32 v[24:25], v[46:47], v[24:25]
	s_nop 0
	v_add_f32_e32 v24, v51, v24
	v_add_f32_e32 v68, v24, v25
	v_lshlrev_b32_e32 v25, 16, v182
	v_lshlrev_b32_e32 v24, 16, v61
	v_pk_mul_f32 v[24:25], v[82:83], v[24:25]
	s_nop 0
	v_add_f32_e32 v24, v40, v24
	v_add_f32_e32 v72, v24, v25
	v_and_b32_e32 v25, 0xffff0000, v182
	v_and_b32_e32 v24, 0xffff0000, v61
	v_pk_mul_f32 v[24:25], v[36:37], v[24:25]
	v_and_b32_e32 v61, 0xffff0000, v183
	v_add_f32_e32 v24, v41, v24
	v_add_f32_e32 v26, v24, v25
	v_lshlrev_b32_e32 v25, 16, v183
	v_lshlrev_b32_e32 v24, 16, v60
	v_pk_mul_f32 v[24:25], v[84:85], v[24:25]
	v_and_b32_e32 v60, 0xffff0000, v60
	v_add_f32_e32 v24, v42, v24
	v_pk_mul_f32 v[60:61], v[38:39], v[60:61]
	v_add_f32_e32 v25, v24, v25
	v_add_f32_e32 v24, v43, v60
	v_add_f32_e32 v24, v24, v61
	s_nop 0
	s_nop 0
	s_nop 1
	v_mov_b32_dpp v184, v172 row_shl:15 row_mask:0xf bank_mask:0xf
	v_mov_b32_dpp v185, v173 row_shl:15 row_mask:0xf bank_mask:0xf
	v_mov_b32_dpp v186, v174 row_shl:15 row_mask:0xf bank_mask:0xf
	v_mov_b32_dpp v187, v175 row_shl:15 row_mask:0xf bank_mask:0xf
	v_mov_b32_dpp v184, v192 row_shr:1 row_mask:0xf bank_mask:0xf
	v_mov_b32_dpp v185, v193 row_shr:1 row_mask:0xf bank_mask:0xf
	v_mov_b32_dpp v186, v194 row_shr:1 row_mask:0xf bank_mask:0xf
	v_mov_b32_dpp v187, v195 row_shr:1 row_mask:0xf bank_mask:0xf
	v_cndmask_b32_e64 v64, 0, v187, s[22:23]
	v_cndmask_b32_e64 v27, 0, v186, s[22:23]
	v_cndmask_b32_e64 v65, 0, v185, s[22:23]
	v_cndmask_b32_e64 v73, 0, v184, s[22:23]
	s_nop 0
	s_nop 0
	v_cndmask_b32_e64 v67, 0, v192, s[10:11]
	v_cndmask_b32_e64 v66, 0, v193, s[10:11]
	v_lshlrev_b32_e32 v61, 16, v67
	v_lshlrev_b32_e32 v60, 16, v73
	v_pk_mul_f32 v[60:61], v[120:121], v[60:61]
	v_cndmask_b32_e64 v194, 0, v194, s[10:11]
	v_add_f32_e32 v60, v70, v60
	v_add_f32_e32 v70, v60, v61
	v_and_b32_e32 v61, 0xffff0000, v67
	v_and_b32_e32 v60, 0xffff0000, v73
	v_pk_mul_f32 v[60:61], v[32:33], v[60:61]
	v_cndmask_b32_e64 v195, 0, v195, s[10:11]
	v_add_f32_e32 v60, v69, v60
	v_add_f32_e32 v67, v60, v61
	v_lshlrev_b32_e32 v61, 16, v66
	v_lshlrev_b32_e32 v60, 16, v65
	v_pk_mul_f32 v[60:61], v[118:119], v[60:61]
	s_nop 0
	v_add_f32_e32 v60, v71, v60
	v_add_f32_e32 v69, v60, v61
	v_and_b32_e32 v61, 0xffff0000, v66
	v_and_b32_e32 v60, 0xffff0000, v65
	v_pk_mul_f32 v[60:61], v[34:35], v[60:61]
	s_nop 0
	v_add_f32_e32 v60, v68, v60
	v_add_f32_e32 v65, v60, v61
	v_lshlrev_b32_e32 v61, 16, v194
	v_lshlrev_b32_e32 v60, 16, v27
	v_pk_mul_f32 v[60:61], v[86:87], v[60:61]
	s_nop 0
	v_add_f32_e32 v60, v72, v60
	v_add_f32_e32 v66, v60, v61
	v_and_b32_e32 v61, 0xffff0000, v194
	v_and_b32_e32 v60, 0xffff0000, v27
	v_pk_mul_f32 v[60:61], v[28:29], v[60:61]
	v_lshlrev_b32_e32 v27, 16, v195
	v_add_f32_e32 v26, v26, v60
	v_add_f32_e32 v60, v26, v61
	v_lshlrev_b32_e32 v26, 16, v64
	v_pk_mul_f32 v[26:27], v[74:75], v[26:27]
	s_nop 0
	v_add_f32_e32 v25, v25, v26
	v_add_f32_e32 v61, v25, v27
	v_and_b32_e32 v27, 0xffff0000, v195
	v_and_b32_e32 v26, 0xffff0000, v64
	v_pk_mul_f32 v[26:27], v[30:31], v[26:27]
	v_cvt_pk_bf16_f32 v25, v69, v65
	s_nop 0
	v_add_f32_e32 v24, v24, v26
	v_add_f32_e32 v27, v24, v27
	v_cvt_pk_bf16_f32 v24, v70, v67
	v_cvt_pk_bf16_f32 v26, v66, v60
	v_cvt_pk_bf16_f32 v27, v61, v27
	s_nop 0
	s_nop 0
	s_nop 1
	v_mov_b32_dpp v212, v192 row_shl:13 row_mask:0xf bank_mask:0xf
	v_mov_b32_dpp v213, v193 row_shl:13 row_mask:0xf bank_mask:0xf
	v_mov_b32_dpp v214, v194 row_shl:13 row_mask:0xf bank_mask:0xf
	v_mov_b32_dpp v215, v195 row_shl:13 row_mask:0xf bank_mask:0xf
	v_mov_b32_dpp v212, v224 row_shr:3 row_mask:0xf bank_mask:0xf
	v_mov_b32_dpp v213, v225 row_shr:3 row_mask:0xf bank_mask:0xf
	v_mov_b32_dpp v214, v226 row_shr:3 row_mask:0xf bank_mask:0xf
	v_mov_b32_dpp v215, v227 row_shr:3 row_mask:0xf bank_mask:0xf
	v_cndmask_b32_e64 v212, 0, v212, s[0:1]
	s_nop 0
	v_cndmask_b32_e64 v213, 0, v213, s[0:1]
	v_cndmask_b32_e64 v214, 0, v214, s[0:1]
	v_cndmask_b32_e64 v215, 0, v215, s[0:1]
	s_nop 0
	s_nop 1
	v_mov_b32_dpp v216, v192 row_shl:14 row_mask:0xf bank_mask:0xf
	v_mov_b32_dpp v217, v193 row_shl:14 row_mask:0xf bank_mask:0xf
	v_mov_b32_dpp v218, v194 row_shl:14 row_mask:0xf bank_mask:0xf
	v_mov_b32_dpp v219, v195 row_shl:14 row_mask:0xf bank_mask:0xf
	v_mov_b32_dpp v216, v224 row_shr:2 row_mask:0xf bank_mask:0xf
	v_mov_b32_dpp v217, v225 row_shr:2 row_mask:0xf bank_mask:0xf
	v_mov_b32_dpp v218, v226 row_shr:2 row_mask:0xf bank_mask:0xf
	v_mov_b32_dpp v219, v227 row_shr:2 row_mask:0xf bank_mask:0xf
	v_cndmask_b32_e64 v65, 0, v216, s[24:25]
	v_cndmask_b32_e64 v64, 0, v217, s[24:25]
	v_lshlrev_b32_e32 v53, 16, v65
	v_lshlrev_b32_e32 v52, 16, v212
	v_pk_mul_f32 v[52:53], v[78:79], v[52:53]
	v_cndmask_b32_e64 v218, 0, v218, s[24:25]
	v_add_f32_e32 v48, v48, v52
	v_add_f32_e32 v48, v48, v53
	v_and_b32_e32 v53, 0xffff0000, v65
	v_and_b32_e32 v52, 0xffff0000, v212
	v_pk_mul_f32 v[44:45], v[44:45], v[52:53]
	v_cndmask_b32_e64 v219, 0, v219, s[24:25]
	v_add_f32_e32 v44, v49, v44
	v_add_f32_e32 v49, v44, v45
	v_lshlrev_b32_e32 v45, 16, v64
	v_lshlrev_b32_e32 v44, 16, v213
	v_pk_mul_f32 v[44:45], v[80:81], v[44:45]
	s_nop 0
	v_add_f32_e32 v44, v50, v44
	v_add_f32_e32 v50, v44, v45
	v_and_b32_e32 v45, 0xffff0000, v64
	v_and_b32_e32 v44, 0xffff0000, v213
	v_pk_mul_f32 v[44:45], v[46:47], v[44:45]
	s_nop 0
	v_add_f32_e32 v44, v51, v44
	v_add_f32_e32 v46, v44, v45
	v_lshlrev_b32_e32 v45, 16, v218
	v_lshlrev_b32_e32 v44, 16, v214
	v_pk_mul_f32 v[44:45], v[82:83], v[44:45]
	s_nop 0
	v_add_f32_e32 v40, v40, v44
	v_add_f32_e32 v47, v40, v45
	v_and_b32_e32 v45, 0xffff0000, v218
	v_and_b32_e32 v44, 0xffff0000, v214
	v_pk_mul_f32 v[36:37], v[36:37], v[44:45]
	v_and_b32_e32 v45, 0xffff0000, v219
	v_add_f32_e32 v36, v41, v36
	v_add_f32_e32 v40, v36, v37
	v_lshlrev_b32_e32 v37, 16, v219
	v_lshlrev_b32_e32 v36, 16, v215
	v_pk_mul_f32 v[36:37], v[84:85], v[36:37]
	v_and_b32_e32 v44, 0xffff0000, v215
	v_add_f32_e32 v36, v42, v36
	v_pk_mul_f32 v[38:39], v[38:39], v[44:45]
	v_add_f32_e32 v37, v36, v37
	v_add_f32_e32 v36, v43, v38
	s_nop 0
	v_add_f32_e32 v36, v36, v39
	s_nop 0
	s_nop 1
	v_mov_b32_dpp v220, v192 row_shl:15 row_mask:0xf bank_mask:0xf
	v_mov_b32_dpp v221, v193 row_shl:15 row_mask:0xf bank_mask:0xf
	v_mov_b32_dpp v222, v194 row_shl:15 row_mask:0xf bank_mask:0xf
	v_mov_b32_dpp v223, v195 row_shl:15 row_mask:0xf bank_mask:0xf
	v_mov_b32_dpp v220, v224 row_shr:1 row_mask:0xf bank_mask:0xf
	v_mov_b32_dpp v221, v225 row_shr:1 row_mask:0xf bank_mask:0xf
	v_mov_b32_dpp v222, v226 row_shr:1 row_mask:0xf bank_mask:0xf
	v_mov_b32_dpp v223, v227 row_shr:1 row_mask:0xf bank_mask:0xf
	v_cndmask_b32_e64 v41, 0, v223, s[26:27]
	v_cndmask_b32_e64 v51, 0, v222, s[26:27]
	v_cndmask_b32_e64 v52, 0, v221, s[26:27]
	v_cndmask_b32_e64 v53, 0, v220, s[26:27]
	s_nop 0
	v_lshlrev_b32_e32 v38, 16, v53
	s_nop 0
	v_cndmask_b32_e64 v224, 0, v224, s[10:11]
	v_lshlrev_b32_e32 v39, 16, v224
	v_pk_mul_f32 v[38:39], v[120:121], v[38:39]
	v_cndmask_b32_e64 v225, 0, v225, s[10:11]
	v_add_f32_e32 v38, v48, v38
	v_add_f32_e32 v48, v38, v39
	v_and_b32_e32 v39, 0xffff0000, v224
	v_and_b32_e32 v38, 0xffff0000, v53
	v_pk_mul_f32 v[32:33], v[32:33], v[38:39]
	v_cndmask_b32_e64 v226, 0, v226, s[10:11]
	v_add_f32_e32 v32, v49, v32
	v_add_f32_e32 v38, v32, v33
	v_lshlrev_b32_e32 v33, 16, v225
	v_lshlrev_b32_e32 v32, 16, v52
	v_pk_mul_f32 v[32:33], v[118:119], v[32:33]
	v_cndmask_b32_e64 v227, 0, v227, s[10:11]
	v_add_f32_e32 v32, v50, v32
	v_add_f32_e32 v39, v32, v33
	v_and_b32_e32 v33, 0xffff0000, v225
	v_and_b32_e32 v32, 0xffff0000, v52
	v_pk_mul_f32 v[32:33], v[34:35], v[32:33]
	s_nop 0
	v_add_f32_e32 v32, v46, v32
	v_add_f32_e32 v34, v32, v33
	v_lshlrev_b32_e32 v33, 16, v226
	v_lshlrev_b32_e32 v32, 16, v51
	v_pk_mul_f32 v[32:33], v[86:87], v[32:33]
	s_nop 0
	v_add_f32_e32 v32, v47, v32
	v_add_f32_e32 v35, v32, v33
	v_and_b32_e32 v33, 0xffff0000, v226
	v_and_b32_e32 v32, 0xffff0000, v51
	v_pk_mul_f32 v[28:29], v[28:29], v[32:33]
	s_nop 0
	v_add_f32_e32 v28, v40, v28
	v_add_f32_e32 v32, v28, v29
	v_lshlrev_b32_e32 v29, 16, v227
	v_lshlrev_b32_e32 v28, 16, v41
	v_pk_mul_f32 v[28:29], v[74:75], v[28:29]
	s_nop 0
	v_add_f32_e32 v28, v37, v28
	v_add_f32_e32 v33, v28, v29
	v_and_b32_e32 v29, 0xffff0000, v227
	v_and_b32_e32 v28, 0xffff0000, v41
	v_pk_mul_f32 v[28:29], v[30:31], v[28:29]
	v_cvt_pk_bf16_f32 v30, v35, v32
	s_nop 0
	v_add_f32_e32 v28, v36, v28
	v_add_f32_e32 v31, v28, v29
	v_cvt_pk_bf16_f32 v28, v48, v38
	v_cvt_pk_bf16_f32 v29, v39, v34
	v_cvt_pk_bf16_f32 v31, v33, v31
	s_lshl_b64 s[80:81], s[80:81], 14
	v_lshl_add_u64 v[120:121], v[100:101], 0, s[78:79]
	v_lshl_add_u64 v[122:123], v[102:103], 0, s[78:79]
	v_lshl_add_u64 v[124:125], v[104:105], 0, s[78:79]
	v_lshl_add_u64 v[126:127], v[106:107], 0, s[78:79]
	v_lshl_add_u64 v[128:129], v[108:109], 0, s[78:79]
	v_readlane_b32 s78, v255, 2
	s_add_u32 s78, s78, s54
	v_readlane_b32 s79, v255, 4
	v_and_or_b32 v32, v202, 64, v92
	s_addc_u32 s79, s79, s55
	v_lshl_or_b32 v184, v32, 2, 60
	v_lshl_add_u64 v[32:33], v[110:111], 0, s[54:55]
	s_add_u32 s54, s68, s54
	s_addc_u32 s55, s69, s55
	v_lshl_add_u64 v[118:119], v[116:117], 0, s[82:83]
	v_lshl_add_u64 v[130:131], s[78:79], 2, v[90:91]
	v_lshl_add_u64 v[132:133], v[32:33], 1, s[66:67]
	v_lshl_add_u64 v[134:135], s[54:55], 1, v[112:113]
	v_lshl_add_u64 v[136:137], v[114:115], 0, s[80:81]
	s_mov_b64 s[78:79], 0
	s_branch .LBB0_195
